# MLA attention: tile barrier issued before the four MFMAs of the last P.V chain (V reads drained first); otherwise as previous
# speedup vs baseline: 1.0410x; 1.0004x over previous
.LBB0_520:
	v_cndmask_b32_e64 v167, v145, v167, s[4:5]
	v_mul_f32_e32 v145, 0xbdd53b94, v167
	v_fmamk_f32 v84, v84, 0x3dd53b94, v145
	v_fmamk_f32 v85, v85, 0x3dd53b94, v145
	v_fmamk_f32 v86, v86, 0x3dd53b94, v145
	v_fmamk_f32 v87, v87, 0x3dd53b94, v145
	v_fmamk_f32 v88, v88, 0x3dd53b94, v145
	v_fmamk_f32 v89, v89, 0x3dd53b94, v145
	v_fmamk_f32 v90, v90, 0x3dd53b94, v145
	v_fmamk_f32 v91, v91, 0x3dd53b94, v145
	v_fmamk_f32 v92, v92, 0x3dd53b94, v145
	v_fmamk_f32 v93, v93, 0x3dd53b94, v145
	v_fmamk_f32 v94, v94, 0x3dd53b94, v145
	v_fmamk_f32 v95, v95, 0x3dd53b94, v145
	v_fmamk_f32 v96, v96, 0x3dd53b94, v145
	v_fmamk_f32 v97, v97, 0x3dd53b94, v145
	v_fmamk_f32 v98, v98, 0x3dd53b94, v145
	v_fmamk_f32 v99, v99, 0x3dd53b94, v145
	v_fmamk_f32 v68, v68, 0x3dd53b94, v145
	v_fmamk_f32 v69, v69, 0x3dd53b94, v145
	v_fmamk_f32 v70, v70, 0x3dd53b94, v145
	v_fmamk_f32 v71, v71, 0x3dd53b94, v145
	v_fmamk_f32 v72, v72, 0x3dd53b94, v145
	v_fmamk_f32 v73, v73, 0x3dd53b94, v145
	v_fmamk_f32 v74, v74, 0x3dd53b94, v145
	v_fmamk_f32 v75, v75, 0x3dd53b94, v145
	v_fmamk_f32 v76, v76, 0x3dd53b94, v145
	v_fmamk_f32 v77, v77, 0x3dd53b94, v145
	v_fmamk_f32 v78, v78, 0x3dd53b94, v145
	v_fmamk_f32 v79, v79, 0x3dd53b94, v145
	v_fmamk_f32 v80, v80, 0x3dd53b94, v145
	v_fmamk_f32 v81, v81, 0x3dd53b94, v145
	v_fmamk_f32 v82, v82, 0x3dd53b94, v145
	v_fmac_f32_e32 v145, 0x3dd53b94, v83
	v_exp_f32_e32 v83, v84
	v_exp_f32_e32 v84, v85
	v_exp_f32_e32 v85, v86
	v_exp_f32_e32 v86, v87
	v_exp_f32_e32 v87, v88
	v_exp_f32_e32 v88, v89
	v_exp_f32_e32 v89, v90
	v_exp_f32_e32 v90, v91
	v_exp_f32_e32 v91, v92
	v_exp_f32_e32 v92, v93
	v_exp_f32_e32 v93, v94
	v_exp_f32_e32 v94, v95
	v_exp_f32_e32 v95, v96
	v_exp_f32_e32 v96, v97
	v_exp_f32_e32 v97, v98
	v_exp_f32_e32 v98, v99
	v_exp_f32_e32 v99, v68
	v_add_f32_e32 v68, 0, v83
	v_add_f32_e32 v68, v84, v68
	v_add_f32_e32 v68, v85, v68
	v_add_f32_e32 v68, v86, v68
	v_add_f32_e32 v68, v87, v68
	v_add_f32_e32 v68, v88, v68
	v_add_f32_e32 v68, v89, v68
	v_add_f32_e32 v68, v90, v68
	v_add_f32_e32 v68, v91, v68
	v_add_f32_e32 v68, v92, v68
	v_add_f32_e32 v68, v93, v68
	v_add_f32_e32 v68, v94, v68
	v_add_f32_e32 v68, v95, v68
	v_exp_f32_e32 v69, v69
	v_add_f32_e32 v68, v96, v68
	v_exp_f32_e32 v147, v70
	v_add_f32_e32 v68, v97, v68
	v_exp_f32_e32 v151, v71
	v_add_f32_e32 v68, v98, v68
	v_exp_f32_e32 v153, v72
	v_add_f32_e32 v68, v99, v68
	v_exp_f32_e32 v169, v73
	v_add_f32_e32 v68, v69, v68
	v_exp_f32_e32 v170, v74
	v_add_f32_e32 v68, v147, v68
	v_exp_f32_e32 v171, v75
	v_add_f32_e32 v68, v151, v68
	v_exp_f32_e32 v172, v76
	v_add_f32_e32 v68, v153, v68
	v_exp_f32_e32 v173, v77
	v_add_f32_e32 v68, v169, v68
	v_exp_f32_e32 v174, v78
	v_add_f32_e32 v68, v170, v68
	v_exp_f32_e32 v175, v79
	v_add_f32_e32 v68, v171, v68
	v_exp_f32_e32 v176, v80
	v_add_f32_e32 v68, v172, v68
	v_exp_f32_e32 v177, v81
	v_add_f32_e32 v68, v173, v68
	v_exp_f32_e32 v178, v82
	v_add_f32_e32 v68, v174, v68
	v_exp_f32_e32 v145, v145
	v_add_f32_e32 v68, v175, v68
	v_add_f32_e32 v68, v176, v68
	v_add_f32_e32 v68, v177, v68
	v_add_f32_e32 v68, v178, v68
	v_add_f32_e32 v68, v145, v68
	v_mov_b32_e32 v70, v68
	s_nop 1
	v_permlane32_swap_b32_e32 v68, v70
	v_add_f32_e32 v68, v68, v70
	v_fmac_f32_e32 v68, v168, v2
	v_cvt_pk_bf16_f32 v70, v83, v84
	v_cvt_pk_bf16_f32 v71, v85, v86
	v_cvt_pk_bf16_f32 v72, v87, v88
	v_cvt_pk_bf16_f32 v73, v89, v90
	v_cvt_pk_bf16_f32 v74, v91, v92
	v_cvt_pk_bf16_f32 v75, v93, v94
	v_cvt_pk_bf16_f32 v76, v95, v96
	v_cvt_pk_bf16_f32 v77, v97, v98
	v_cvt_pk_bf16_f32 v78, v99, v69
	v_cvt_pk_bf16_f32 v79, v147, v151
	v_cvt_pk_bf16_f32 v80, v153, v169
	v_cvt_pk_bf16_f32 v81, v170, v171
	v_cvt_pk_bf16_f32 v82, v172, v173
	v_cvt_pk_bf16_f32 v83, v174, v175
	v_cvt_pk_bf16_f32 v84, v176, v177
	v_cvt_pk_bf16_f32 v85, v178, v145
	v_permlane32_swap_b32_e32 v70, v72
	v_permlane32_swap_b32_e32 v71, v73
	v_permlane32_swap_b32_e32 v74, v76
	v_permlane32_swap_b32_e32 v75, v77
	v_permlane32_swap_b32_e32 v78, v80
	v_permlane32_swap_b32_e32 v79, v81
	v_permlane32_swap_b32_e32 v82, v84
	v_permlane32_swap_b32_e32 v83, v85
	v_add_u32_e32 v2, s33, v166
	ds_read_b64_tr_b16 v[86:87], v2 offset:0
	ds_read_b64_tr_b16 v[88:89], v2 offset:0x800
	ds_read_b64_tr_b16 v[90:91], v2 offset:0x1000
	ds_read_b64_tr_b16 v[92:93], v2 offset:0x1800
	ds_read_b64_tr_b16 v[94:95], v2 offset:0x2000
	ds_read_b64_tr_b16 v[96:97], v2 offset:0x2800
	ds_read_b64_tr_b16 v[168:169], v2 offset:0x3000
	ds_read_b64_tr_b16 v[170:171], v2 offset:0x3800
	s_waitcnt lgkmcnt(6)
	s_nop 0
	v_mfma_f32_32x32x16_bf16 v[52:67], v[70:73], v[86:89], v[52:67]
	ds_read_b64_tr_b16 v[86:87], v2 offset:0x200
	ds_read_b64_tr_b16 v[88:89], v2 offset:0xa00
	s_waitcnt lgkmcnt(6)
	v_mfma_f32_32x32x16_bf16 v[52:67], v[74:77], v[90:93], v[52:67]
	ds_read_b64_tr_b16 v[90:91], v2 offset:0x1200
	ds_read_b64_tr_b16 v[92:93], v2 offset:0x1a00
	s_waitcnt lgkmcnt(6)
	v_mfma_f32_32x32x16_bf16 v[52:67], v[78:81], v[94:97], v[52:67]
	ds_read_b64_tr_b16 v[94:95], v2 offset:0x2200
	ds_read_b64_tr_b16 v[96:97], v2 offset:0x2a00
	s_waitcnt lgkmcnt(6)
	v_mfma_f32_32x32x16_bf16 v[52:67], v[82:85], v[168:171], v[52:67]
	ds_read_b64_tr_b16 v[168:169], v2 offset:0x3200
	ds_read_b64_tr_b16 v[170:171], v2 offset:0x3a00
	s_waitcnt lgkmcnt(6)
	v_mfma_f32_32x32x16_bf16 v[36:51], v[70:73], v[86:89], v[36:51]
	ds_read_b64_tr_b16 v[86:87], v2 offset:0x400
	ds_read_b64_tr_b16 v[88:89], v2 offset:0xc00
	s_waitcnt lgkmcnt(6)
	v_mfma_f32_32x32x16_bf16 v[36:51], v[74:77], v[90:93], v[36:51]
	ds_read_b64_tr_b16 v[90:91], v2 offset:0x1400
	ds_read_b64_tr_b16 v[92:93], v2 offset:0x1c00
	s_waitcnt lgkmcnt(6)
	v_mfma_f32_32x32x16_bf16 v[36:51], v[78:81], v[94:97], v[36:51]
	ds_read_b64_tr_b16 v[94:95], v2 offset:0x2400
	ds_read_b64_tr_b16 v[96:97], v2 offset:0x2c00
	s_waitcnt lgkmcnt(6)
	v_mfma_f32_32x32x16_bf16 v[36:51], v[82:85], v[168:171], v[36:51]
	ds_read_b64_tr_b16 v[168:169], v2 offset:0x3400
	ds_read_b64_tr_b16 v[170:171], v2 offset:0x3c00
	s_waitcnt lgkmcnt(6)
	v_mfma_f32_32x32x16_bf16 v[20:35], v[70:73], v[86:89], v[20:35]
	ds_read_b64_tr_b16 v[86:87], v2 offset:0x600
	ds_read_b64_tr_b16 v[88:89], v2 offset:0xe00
	s_waitcnt lgkmcnt(6)
	v_mfma_f32_32x32x16_bf16 v[20:35], v[74:77], v[90:93], v[20:35]
	ds_read_b64_tr_b16 v[90:91], v2 offset:0x1600
	ds_read_b64_tr_b16 v[92:93], v2 offset:0x1e00
	s_waitcnt lgkmcnt(6)
	v_mfma_f32_32x32x16_bf16 v[20:35], v[78:81], v[94:97], v[20:35]
	ds_read_b64_tr_b16 v[94:95], v2 offset:0x2600
	ds_read_b64_tr_b16 v[96:97], v2 offset:0x2e00
	s_waitcnt lgkmcnt(6)
	v_mfma_f32_32x32x16_bf16 v[20:35], v[82:85], v[168:171], v[20:35]
	ds_read_b64_tr_b16 v[168:169], v2 offset:0x3600
	ds_read_b64_tr_b16 v[170:171], v2 offset:0x3e00
	s_waitcnt vmcnt(0) lgkmcnt(0)
	s_cmpk_eq_i32 s31, 0x48
	s_waitcnt vmcnt(0)
	s_barrier
	v_mfma_f32_32x32x16_bf16 v[4:19], v[70:73], v[86:89], v[4:19]
	v_mfma_f32_32x32x16_bf16 v[4:19], v[74:77], v[90:93], v[4:19]
	v_mfma_f32_32x32x16_bf16 v[4:19], v[78:81], v[94:97], v[4:19]
	v_mfma_f32_32x32x16_bf16 v[4:19], v[82:85], v[168:171], v[4:19]
	s_cbranch_scc0 .LBB0_512
	s_and_saveexec_b64 s[4:5], s[0:1]
	s_cbranch_execz .LBB0_497
	ds_write_b32 v159, v68
	s_branch .LBB0_497
